# diff attention body: two wait+barrier pairs removed where the code that follows already waits and synchronises (pass boundary and unit exit)
# baseline (speedup 1.0000x reference)
; __device__ __forceinline__ int crow(int r,int hi){return (r&3)+8*(r>>2)+4*hi;}
; __device__ __forceinline__ unsigned cvtpk_s(float lo,float hi){f32x2_t v={lo,hi};bf16x2_t b=__builtin_convertvector(v,bf16x2_t);return __builtin_bit_cast(unsigned,b);}
;     ...
;   {auto rr=__builtin_amdgcn_permlane32_swap(__float_as_uint(l_reg),__float_as_uint(l_reg),false,false);l_reg=__uint_as_float(rr[0])+__uint_as_float(rr[1]);}
;   if(hi==0)wsf[32+r32]=l_reg;asm volatile("s_waitcnt lgkmcnt(0)":::"memory");
;   float rli[16];
;   #pragma unroll
;   for(int r=0;r<16;++r)rli[r]=__builtin_amdgcn_rcpf(wsf[32+crow(r,hi)]);
;   bf16*Ow=Ob+(long)(wid*QBLK)*OP;
;   { bf16*stg=(bf16*)(shm+LDS_OST+wid*MWAVE);
;     bf16*stl=stg+bsel*2048+hi*256+r32;
;     if(emode>=2){
;       #pragma unroll
;       for(int r=0;r<16;++r){
;         #pragma unroll
;         for(int d0=0;d0<2;++d0){ const float old=__uint_as_float((unsigned)stl[cr0(r)*64+d0*32]<<16); stl[cr0(r)*64+d0*32]=(bf16)(cvtpk_s(old-lam*(o[d0][r]*rli[r]),0.f)&0xffffu);} }
;     } else {
;       #pragma unroll
;       for(int r=0;r<16;++r){
;         #pragma unroll
;         for(int d0=0;d0<2;++d0)stl[cr0(r)*64+d0*32]=(bf16)(cvtpk_s(o[d0][r]*rli[r],0.f)&0xffffu);}
;     }
.Lfd_drain2:
	s_barrier
	s_nop 7
	s_nop 7
	v_mov_b32_e32 v4, v34
	v_mov_b32_e32 v5, v34
	s_nop 1
	v_permlane32_swap_b32_e32 v4, v5
	v_add_f32_e32 v4, v4, v5
	ds_write_b32 v44, v4 offset:128
	s_waitcnt lgkmcnt(0)
	ds_read_b128 v[112:115], v45 offset:128
	ds_read_b128 v[116:119], v45 offset:160
	ds_read_b128 v[120:123], v45 offset:192
	ds_read_b128 v[124:127], v45 offset:224
	s_waitcnt lgkmcnt(0)
	v_rcp_f32_e32 v112, v112
	v_rcp_f32_e32 v113, v113
	v_rcp_f32_e32 v114, v114
	v_rcp_f32_e32 v115, v115
	v_rcp_f32_e32 v116, v116
	v_rcp_f32_e32 v117, v117
	v_rcp_f32_e32 v118, v118
	v_rcp_f32_e32 v119, v119
	v_rcp_f32_e32 v120, v120
	v_rcp_f32_e32 v121, v121
	v_rcp_f32_e32 v122, v122
	v_rcp_f32_e32 v123, v123
	v_rcp_f32_e32 v124, v124
	v_rcp_f32_e32 v125, v125
	v_rcp_f32_e32 v126, v126
	v_rcp_f32_e32 v127, v127
	s_nop 0
	s_cmp_lg_u32 s90, 0
	s_cbranch_scc1 .Lfd_epi1
	v_mul_f32_e32 v4, v48, v112
	v_cvt_pk_bf16_f32 v4, v4, v4
	ds_write_b16 v46, v4 offset:0
	v_mul_f32_e32 v4, v49, v113
	v_cvt_pk_bf16_f32 v4, v4, v4
	ds_write_b16 v46, v4 offset:256
	v_mul_f32_e32 v4, v50, v114
	v_cvt_pk_bf16_f32 v4, v4, v4
	ds_write_b16 v46, v4 offset:512
	v_mul_f32_e32 v4, v51, v115
	v_cvt_pk_bf16_f32 v4, v4, v4
	ds_write_b16 v46, v4 offset:768
	v_mul_f32_e32 v4, v52, v116
	v_cvt_pk_bf16_f32 v4, v4, v4
	ds_write_b16 v46, v4 offset:2048
	v_mul_f32_e32 v4, v53, v117
	v_cvt_pk_bf16_f32 v4, v4, v4
	ds_write_b16 v46, v4 offset:2304
	v_mul_f32_e32 v4, v54, v118
	v_cvt_pk_bf16_f32 v4, v4, v4
	ds_write_b16 v46, v4 offset:2560
	v_mul_f32_e32 v4, v55, v119
	v_cvt_pk_bf16_f32 v4, v4, v4
	ds_write_b16 v46, v4 offset:2816
	v_mul_f32_e32 v4, v56, v120
	v_cvt_pk_bf16_f32 v4, v4, v4
	ds_write_b16 v46, v4 offset:4096
	v_mul_f32_e32 v4, v57, v121
	v_cvt_pk_bf16_f32 v4, v4, v4
	ds_write_b16 v46, v4 offset:4352
	v_mul_f32_e32 v4, v58, v122
	v_cvt_pk_bf16_f32 v4, v4, v4
	ds_write_b16 v46, v4 offset:4608
	v_mul_f32_e32 v4, v59, v123
	v_cvt_pk_bf16_f32 v4, v4, v4
	ds_write_b16 v46, v4 offset:4864
	v_mul_f32_e32 v4, v60, v124
	v_cvt_pk_bf16_f32 v4, v4, v4
	ds_write_b16 v46, v4 offset:6144
	v_mul_f32_e32 v4, v61, v125
	v_cvt_pk_bf16_f32 v4, v4, v4
	ds_write_b16 v46, v4 offset:6400
	v_mul_f32_e32 v4, v62, v126
	v_cvt_pk_bf16_f32 v4, v4, v4
	ds_write_b16 v46, v4 offset:6656
	v_mul_f32_e32 v4, v63, v127
	v_cvt_pk_bf16_f32 v4, v4, v4
	ds_write_b16 v46, v4 offset:6912
	v_mul_f32_e32 v4, v64, v112
	v_cvt_pk_bf16_f32 v4, v4, v4
	ds_write_b16 v46, v4 offset:64
	v_mul_f32_e32 v4, v65, v113
	v_cvt_pk_bf16_f32 v4, v4, v4
	ds_write_b16 v46, v4 offset:320
	v_mul_f32_e32 v4, v66, v114
	v_cvt_pk_bf16_f32 v4, v4, v4
	ds_write_b16 v46, v4 offset:576
	v_mul_f32_e32 v4, v67, v115
	v_cvt_pk_bf16_f32 v4, v4, v4
	ds_write_b16 v46, v4 offset:832
	v_mul_f32_e32 v4, v68, v116
	v_cvt_pk_bf16_f32 v4, v4, v4
	ds_write_b16 v46, v4 offset:2112
	v_mul_f32_e32 v4, v69, v117
	v_cvt_pk_bf16_f32 v4, v4, v4
	ds_write_b16 v46, v4 offset:2368
	v_mul_f32_e32 v4, v70, v118
	v_cvt_pk_bf16_f32 v4, v4, v4
	ds_write_b16 v46, v4 offset:2624
	v_mul_f32_e32 v4, v71, v119
	v_cvt_pk_bf16_f32 v4, v4, v4
	ds_write_b16 v46, v4 offset:2880
	v_mul_f32_e32 v4, v72, v120
	v_cvt_pk_bf16_f32 v4, v4, v4
	ds_write_b16 v46, v4 offset:4160
	v_mul_f32_e32 v4, v73, v121
	v_cvt_pk_bf16_f32 v4, v4, v4
	ds_write_b16 v46, v4 offset:4416
	v_mul_f32_e32 v4, v74, v122
	v_cvt_pk_bf16_f32 v4, v4, v4
	ds_write_b16 v46, v4 offset:4672
	v_mul_f32_e32 v4, v75, v123
	v_cvt_pk_bf16_f32 v4, v4, v4
	ds_write_b16 v46, v4 offset:4928
	v_mul_f32_e32 v4, v76, v124
	v_cvt_pk_bf16_f32 v4, v4, v4
	ds_write_b16 v46, v4 offset:6208
	v_mul_f32_e32 v4, v77, v125
	v_cvt_pk_bf16_f32 v4, v4, v4
	ds_write_b16 v46, v4 offset:6464
	v_mul_f32_e32 v4, v78, v126
	v_cvt_pk_bf16_f32 v4, v4, v4
	ds_write_b16 v46, v4 offset:6720
	v_mul_f32_e32 v4, v79, v127
	v_cvt_pk_bf16_f32 v4, v4, v4
	ds_write_b16 v46, v4 offset:6976
	v_mul_f32_e32 v4, v80, v112
	v_cvt_pk_bf16_f32 v4, v4, v4
	ds_write_b16 v46, v4 offset:128
	v_mul_f32_e32 v4, v81, v113
	v_cvt_pk_bf16_f32 v4, v4, v4
	ds_write_b16 v46, v4 offset:384
	v_mul_f32_e32 v4, v82, v114
	v_cvt_pk_bf16_f32 v4, v4, v4
	ds_write_b16 v46, v4 offset:640
	v_mul_f32_e32 v4, v83, v115
	v_cvt_pk_bf16_f32 v4, v4, v4
	ds_write_b16 v46, v4 offset:896
	v_mul_f32_e32 v4, v84, v116
	v_cvt_pk_bf16_f32 v4, v4, v4
	ds_write_b16 v46, v4 offset:2176
	v_mul_f32_e32 v4, v85, v117
	v_cvt_pk_bf16_f32 v4, v4, v4
	ds_write_b16 v46, v4 offset:2432
	v_mul_f32_e32 v4, v86, v118
	v_cvt_pk_bf16_f32 v4, v4, v4
	ds_write_b16 v46, v4 offset:2688
	v_mul_f32_e32 v4, v87, v119
	v_cvt_pk_bf16_f32 v4, v4, v4
	ds_write_b16 v46, v4 offset:2944
	v_mul_f32_e32 v4, v88, v120
	v_cvt_pk_bf16_f32 v4, v4, v4
	ds_write_b16 v46, v4 offset:4224
	v_mul_f32_e32 v4, v89, v121
	v_cvt_pk_bf16_f32 v4, v4, v4
	ds_write_b16 v46, v4 offset:4480
	v_mul_f32_e32 v4, v90, v122
	v_cvt_pk_bf16_f32 v4, v4, v4
	ds_write_b16 v46, v4 offset:4736
	v_mul_f32_e32 v4, v91, v123
	v_cvt_pk_bf16_f32 v4, v4, v4
	ds_write_b16 v46, v4 offset:4992
	v_mul_f32_e32 v4, v92, v124
	v_cvt_pk_bf16_f32 v4, v4, v4
	ds_write_b16 v46, v4 offset:6272
	v_mul_f32_e32 v4, v93, v125
	v_cvt_pk_bf16_f32 v4, v4, v4
	ds_write_b16 v46, v4 offset:6528
	v_mul_f32_e32 v4, v94, v126
	v_cvt_pk_bf16_f32 v4, v4, v4
	ds_write_b16 v46, v4 offset:6784
	v_mul_f32_e32 v4, v95, v127
	v_cvt_pk_bf16_f32 v4, v4, v4
	ds_write_b16 v46, v4 offset:7040
	v_mul_f32_e32 v4, v96, v112
	v_cvt_pk_bf16_f32 v4, v4, v4
	ds_write_b16 v46, v4 offset:192
	v_mul_f32_e32 v4, v97, v113
	v_cvt_pk_bf16_f32 v4, v4, v4
	ds_write_b16 v46, v4 offset:448
	v_mul_f32_e32 v4, v98, v114
	v_cvt_pk_bf16_f32 v4, v4, v4
	ds_write_b16 v46, v4 offset:704
	v_mul_f32_e32 v4, v99, v115
	v_cvt_pk_bf16_f32 v4, v4, v4
	ds_write_b16 v46, v4 offset:960
	v_mul_f32_e32 v4, v100, v116
	v_cvt_pk_bf16_f32 v4, v4, v4
	ds_write_b16 v46, v4 offset:2240
	v_mul_f32_e32 v4, v101, v117
	v_cvt_pk_bf16_f32 v4, v4, v4
	ds_write_b16 v46, v4 offset:2496
	v_mul_f32_e32 v4, v102, v118
	v_cvt_pk_bf16_f32 v4, v4, v4
	ds_write_b16 v46, v4 offset:2752
	v_mul_f32_e32 v4, v103, v119
	v_cvt_pk_bf16_f32 v4, v4, v4
	ds_write_b16 v46, v4 offset:3008
	v_mul_f32_e32 v4, v104, v120
	v_cvt_pk_bf16_f32 v4, v4, v4
	ds_write_b16 v46, v4 offset:4288
	v_mul_f32_e32 v4, v105, v121
	v_cvt_pk_bf16_f32 v4, v4, v4
	ds_write_b16 v46, v4 offset:4544
	v_mul_f32_e32 v4, v106, v122
	v_cvt_pk_bf16_f32 v4, v4, v4
	ds_write_b16 v46, v4 offset:4800
	v_mul_f32_e32 v4, v107, v123
	v_cvt_pk_bf16_f32 v4, v4, v4
	ds_write_b16 v46, v4 offset:5056
	v_mul_f32_e32 v4, v108, v124
	v_cvt_pk_bf16_f32 v4, v4, v4
	ds_write_b16 v46, v4 offset:6336
	v_mul_f32_e32 v4, v109, v125
	v_cvt_pk_bf16_f32 v4, v4, v4
	ds_write_b16 v46, v4 offset:6592
	v_mul_f32_e32 v4, v110, v126
	v_cvt_pk_bf16_f32 v4, v4, v4
	ds_write_b16 v46, v4 offset:6848
	v_mul_f32_e32 v4, v111, v127
	v_cvt_pk_bf16_f32 v4, v4, v4
	ds_write_b16 v46, v4 offset:7104
	s_waitcnt lgkmcnt(0)
; __device__ __forceinline__ unsigned cvtpk_s(float lo,float hi){f32x2_t v={lo,hi};bf16x2_t b=__builtin_convertvector(v,bf16x2_t);return __builtin_bit_cast(unsigned,b);}
; #define ATTN_STORE16(p,v) st16_wt((p),(v))
;     ...
;     if(emode>=2){
;       #pragma unroll
;       for(int r=0;r<16;++r){
;         #pragma unroll
;         for(int d0=0;d0<2;++d0){ const float old=__uint_as_float((unsigned)stl[cr0(r)*64+d0*32]<<16); stl[cr0(r)*64+d0*32]=(bf16)(cvtpk_s(old-lam*(o[d0][r]*rli[r]),0.f)&0xffffu);} }
;     } else {
;       #pragma unroll
;       for(int r=0;r<16;++r){
;         #pragma unroll
;         for(int d0=0;d0<2;++d0)stl[cr0(r)*64+d0*32]=(bf16)(cvtpk_s(o[d0][r]*rli[r],0.f)&0xffffu);}
;     }
;     asm volatile("s_waitcnt lgkmcnt(0)":::"memory");
;     if(emode==0){
;       #pragma unroll
;       for(int i=0;i<4;++i){const int row=i*8+(lane>>3),ch=lane&7; const u32x4 v=*(const u32x4*)(stg+row*64+ch*8); ATTN_STORE16(Ow+(long)row*OP+ch*8,v);}
	ds_read_b128 v[176:179], v219 offset:0
	ds_read_b128 v[180:183], v219 offset:1024
	ds_read_b128 v[184:187], v219 offset:2048
	ds_read_b128 v[188:191], v219 offset:3072
	ds_read_b128 v[192:195], v219 offset:4096
	ds_read_b128 v[196:199], v219 offset:5120
	ds_read_b128 v[200:203], v219 offset:6144
	ds_read_b128 v[204:207], v219 offset:7168
	s_waitcnt lgkmcnt(0)
	v_mov_b32_e32 v253, v252
	global_store_dwordx4 v253, v[176:179], s[86:87]
	v_add_u32_e32 v253, 0x2000, v253
	global_store_dwordx4 v253, v[180:183], s[86:87]
	v_add_u32_e32 v253, 0x2000, v253
	global_store_dwordx4 v253, v[184:187], s[86:87]
	v_add_u32_e32 v253, 0x2000, v253
	global_store_dwordx4 v253, v[188:191], s[86:87]
	v_add_u32_e32 v253, 0x2000, v253
	global_store_dwordx4 v253, v[192:195], s[86:87]
	v_add_u32_e32 v253, 0x2000, v253
	global_store_dwordx4 v253, v[196:199], s[86:87]
	v_add_u32_e32 v253, 0x2000, v253
	global_store_dwordx4 v253, v[200:203], s[86:87]
	v_add_u32_e32 v253, 0x2000, v253
	global_store_dwordx4 v253, v[204:207], s[86:87]
	s_mov_b32 s90, 1
	s_branch .Lfd_pass
.Lfd_epi1:
	v_mov_b32_e32 v253, v252
	global_load_dwordx4 v[176:179], v253, s[86:87]
	v_add_u32_e32 v253, 0x2000, v253
	global_load_dwordx4 v[180:183], v253, s[86:87]
	v_add_u32_e32 v253, 0x2000, v253
	global_load_dwordx4 v[184:187], v253, s[86:87]
	v_add_u32_e32 v253, 0x2000, v253
	global_load_dwordx4 v[188:191], v253, s[86:87]
	v_add_u32_e32 v253, 0x2000, v253
	global_load_dwordx4 v[192:195], v253, s[86:87]
	v_add_u32_e32 v253, 0x2000, v253
	global_load_dwordx4 v[196:199], v253, s[86:87]
	v_add_u32_e32 v253, 0x2000, v253
	global_load_dwordx4 v[200:203], v253, s[86:87]
	v_add_u32_e32 v253, 0x2000, v253
	global_load_dwordx4 v[204:207], v253, s[86:87]
	s_waitcnt vmcnt(0)
	ds_write_b128 v219, v[176:179] offset:0
	ds_write_b128 v219, v[180:183] offset:1024
	ds_write_b128 v219, v[184:187] offset:2048
	ds_write_b128 v219, v[188:191] offset:3072
	ds_write_b128 v219, v[192:195] offset:4096
	ds_write_b128 v219, v[196:199] offset:5120
	ds_write_b128 v219, v[200:203] offset:6144
	ds_write_b128 v219, v[204:207] offset:7168
	s_waitcnt lgkmcnt(0)
	ds_read_u16 v128, v46 offset:0
	ds_read_u16 v129, v46 offset:256
	ds_read_u16 v130, v46 offset:512
	ds_read_u16 v131, v46 offset:768
	ds_read_u16 v132, v46 offset:2048
	ds_read_u16 v133, v46 offset:2304
	ds_read_u16 v134, v46 offset:2560
	ds_read_u16 v135, v46 offset:2816
	ds_read_u16 v136, v46 offset:4096
	ds_read_u16 v137, v46 offset:4352
	ds_read_u16 v138, v46 offset:4608
	ds_read_u16 v139, v46 offset:4864
	ds_read_u16 v140, v46 offset:6144
	ds_read_u16 v141, v46 offset:6400
	ds_read_u16 v142, v46 offset:6656
	ds_read_u16 v143, v46 offset:6912
	s_waitcnt lgkmcnt(0)
	v_mul_f32_e32 v4, v48, v112
	v_lshlrev_b32_e32 v5, 16, v128
	v_fma_f32 v4, -v216, v4, v5
	v_cvt_pk_bf16_f32 v4, v4, v4
	ds_write_b16 v46, v4 offset:0
	v_mul_f32_e32 v4, v49, v113
	v_lshlrev_b32_e32 v5, 16, v129
	v_fma_f32 v4, -v216, v4, v5
	v_cvt_pk_bf16_f32 v4, v4, v4
	ds_write_b16 v46, v4 offset:256
	v_mul_f32_e32 v4, v50, v114
	v_lshlrev_b32_e32 v5, 16, v130
	v_fma_f32 v4, -v216, v4, v5
	v_cvt_pk_bf16_f32 v4, v4, v4
	ds_write_b16 v46, v4 offset:512
	v_mul_f32_e32 v4, v51, v115
	v_lshlrev_b32_e32 v5, 16, v131
	v_fma_f32 v4, -v216, v4, v5
	v_cvt_pk_bf16_f32 v4, v4, v4
	ds_write_b16 v46, v4 offset:768
	v_mul_f32_e32 v4, v52, v116
	v_lshlrev_b32_e32 v5, 16, v132
	v_fma_f32 v4, -v216, v4, v5
	v_cvt_pk_bf16_f32 v4, v4, v4
	ds_write_b16 v46, v4 offset:2048
	v_mul_f32_e32 v4, v53, v117
	v_lshlrev_b32_e32 v5, 16, v133
	v_fma_f32 v4, -v216, v4, v5
	v_cvt_pk_bf16_f32 v4, v4, v4
	ds_write_b16 v46, v4 offset:2304
	v_mul_f32_e32 v4, v54, v118
	v_lshlrev_b32_e32 v5, 16, v134
	v_fma_f32 v4, -v216, v4, v5
	v_cvt_pk_bf16_f32 v4, v4, v4
	ds_write_b16 v46, v4 offset:2560
	v_mul_f32_e32 v4, v55, v119
	v_lshlrev_b32_e32 v5, 16, v135
	v_fma_f32 v4, -v216, v4, v5
	v_cvt_pk_bf16_f32 v4, v4, v4
	ds_write_b16 v46, v4 offset:2816
	v_mul_f32_e32 v4, v56, v120
	v_lshlrev_b32_e32 v5, 16, v136
	v_fma_f32 v4, -v216, v4, v5
	v_cvt_pk_bf16_f32 v4, v4, v4
	ds_write_b16 v46, v4 offset:4096
	v_mul_f32_e32 v4, v57, v121
	v_lshlrev_b32_e32 v5, 16, v137
	v_fma_f32 v4, -v216, v4, v5
	v_cvt_pk_bf16_f32 v4, v4, v4
	ds_write_b16 v46, v4 offset:4352
	v_mul_f32_e32 v4, v58, v122
	v_lshlrev_b32_e32 v5, 16, v138
	v_fma_f32 v4, -v216, v4, v5
	v_cvt_pk_bf16_f32 v4, v4, v4
	ds_write_b16 v46, v4 offset:4608
	v_mul_f32_e32 v4, v59, v123
	v_lshlrev_b32_e32 v5, 16, v139
	v_fma_f32 v4, -v216, v4, v5
	v_cvt_pk_bf16_f32 v4, v4, v4
	ds_write_b16 v46, v4 offset:4864
	v_mul_f32_e32 v4, v60, v124
	v_lshlrev_b32_e32 v5, 16, v140
	v_fma_f32 v4, -v216, v4, v5
	v_cvt_pk_bf16_f32 v4, v4, v4
	ds_write_b16 v46, v4 offset:6144
	v_mul_f32_e32 v4, v61, v125
	v_lshlrev_b32_e32 v5, 16, v141
	v_fma_f32 v4, -v216, v4, v5
	v_cvt_pk_bf16_f32 v4, v4, v4
	ds_write_b16 v46, v4 offset:6400
	v_mul_f32_e32 v4, v62, v126
	v_lshlrev_b32_e32 v5, 16, v142
	v_fma_f32 v4, -v216, v4, v5
	v_cvt_pk_bf16_f32 v4, v4, v4
	ds_write_b16 v46, v4 offset:6656
	v_mul_f32_e32 v4, v63, v127
	v_lshlrev_b32_e32 v5, 16, v143
	v_fma_f32 v4, -v216, v4, v5
	v_cvt_pk_bf16_f32 v4, v4, v4
	ds_write_b16 v46, v4 offset:6912
	ds_read_u16 v128, v46 offset:64
	ds_read_u16 v129, v46 offset:320
	ds_read_u16 v130, v46 offset:576
	ds_read_u16 v131, v46 offset:832
	ds_read_u16 v132, v46 offset:2112
	ds_read_u16 v133, v46 offset:2368
	ds_read_u16 v134, v46 offset:2624
	ds_read_u16 v135, v46 offset:2880
	ds_read_u16 v136, v46 offset:4160
	ds_read_u16 v137, v46 offset:4416
	ds_read_u16 v138, v46 offset:4672
	ds_read_u16 v139, v46 offset:4928
	ds_read_u16 v140, v46 offset:6208
	ds_read_u16 v141, v46 offset:6464
	ds_read_u16 v142, v46 offset:6720
	ds_read_u16 v143, v46 offset:6976
	s_waitcnt lgkmcnt(0)
; __device__ __forceinline__ unsigned cvtpk_s(float lo,float hi){f32x2_t v={lo,hi};bf16x2_t b=__builtin_convertvector(v,bf16x2_t);return __builtin_bit_cast(unsigned,b);}
;     ...
;     if(emode>=2){
;       #pragma unroll
;       for(int r=0;r<16;++r){
;         #pragma unroll
;         for(int d0=0;d0<2;++d0){ const float old=__uint_as_float((unsigned)stl[cr0(r)*64+d0*32]<<16); stl[cr0(r)*64+d0*32]=(bf16)(cvtpk_s(old-lam*(o[d0][r]*rli[r]),0.f)&0xffffu);} }
	v_mul_f32_e32 v4, v64, v112
	v_lshlrev_b32_e32 v5, 16, v128
	v_fma_f32 v4, -v216, v4, v5
	v_cvt_pk_bf16_f32 v4, v4, v4
	ds_write_b16 v46, v4 offset:64
	v_mul_f32_e32 v4, v65, v113
	v_lshlrev_b32_e32 v5, 16, v129
	v_fma_f32 v4, -v216, v4, v5
	v_cvt_pk_bf16_f32 v4, v4, v4
	ds_write_b16 v46, v4 offset:320
	v_mul_f32_e32 v4, v66, v114
	v_lshlrev_b32_e32 v5, 16, v130
	v_fma_f32 v4, -v216, v4, v5
	v_cvt_pk_bf16_f32 v4, v4, v4
	ds_write_b16 v46, v4 offset:576
	v_mul_f32_e32 v4, v67, v115
	v_lshlrev_b32_e32 v5, 16, v131
	v_fma_f32 v4, -v216, v4, v5
	v_cvt_pk_bf16_f32 v4, v4, v4
	ds_write_b16 v46, v4 offset:832
	v_mul_f32_e32 v4, v68, v116
	v_lshlrev_b32_e32 v5, 16, v132
	v_fma_f32 v4, -v216, v4, v5
	v_cvt_pk_bf16_f32 v4, v4, v4
	ds_write_b16 v46, v4 offset:2112
	v_mul_f32_e32 v4, v69, v117
	v_lshlrev_b32_e32 v5, 16, v133
	v_fma_f32 v4, -v216, v4, v5
	v_cvt_pk_bf16_f32 v4, v4, v4
	ds_write_b16 v46, v4 offset:2368
	v_mul_f32_e32 v4, v70, v118
	v_lshlrev_b32_e32 v5, 16, v134
	v_fma_f32 v4, -v216, v4, v5
	v_cvt_pk_bf16_f32 v4, v4, v4
	ds_write_b16 v46, v4 offset:2624
	v_mul_f32_e32 v4, v71, v119
	v_lshlrev_b32_e32 v5, 16, v135
	v_fma_f32 v4, -v216, v4, v5
	v_cvt_pk_bf16_f32 v4, v4, v4
	ds_write_b16 v46, v4 offset:2880
	v_mul_f32_e32 v4, v72, v120
	v_lshlrev_b32_e32 v5, 16, v136
	v_fma_f32 v4, -v216, v4, v5
	v_cvt_pk_bf16_f32 v4, v4, v4
	ds_write_b16 v46, v4 offset:4160
	v_mul_f32_e32 v4, v73, v121
	v_lshlrev_b32_e32 v5, 16, v137
	v_fma_f32 v4, -v216, v4, v5
	v_cvt_pk_bf16_f32 v4, v4, v4
	ds_write_b16 v46, v4 offset:4416
	v_mul_f32_e32 v4, v74, v122
	v_lshlrev_b32_e32 v5, 16, v138
	v_fma_f32 v4, -v216, v4, v5
	v_cvt_pk_bf16_f32 v4, v4, v4
	ds_write_b16 v46, v4 offset:4672
	v_mul_f32_e32 v4, v75, v123
	v_lshlrev_b32_e32 v5, 16, v139
	v_fma_f32 v4, -v216, v4, v5
	v_cvt_pk_bf16_f32 v4, v4, v4
	ds_write_b16 v46, v4 offset:4928
	v_mul_f32_e32 v4, v76, v124
	v_lshlrev_b32_e32 v5, 16, v140
	v_fma_f32 v4, -v216, v4, v5
	v_cvt_pk_bf16_f32 v4, v4, v4
	ds_write_b16 v46, v4 offset:6208
	v_mul_f32_e32 v4, v77, v125
	v_lshlrev_b32_e32 v5, 16, v141
	v_fma_f32 v4, -v216, v4, v5
	v_cvt_pk_bf16_f32 v4, v4, v4
	ds_write_b16 v46, v4 offset:6464
	v_mul_f32_e32 v4, v78, v126
	v_lshlrev_b32_e32 v5, 16, v142
	v_fma_f32 v4, -v216, v4, v5
	v_cvt_pk_bf16_f32 v4, v4, v4
	ds_write_b16 v46, v4 offset:6720
	v_mul_f32_e32 v4, v79, v127
	v_lshlrev_b32_e32 v5, 16, v143
	v_fma_f32 v4, -v216, v4, v5
	v_cvt_pk_bf16_f32 v4, v4, v4
	ds_write_b16 v46, v4 offset:6976
	ds_read_u16 v128, v46 offset:128
	ds_read_u16 v129, v46 offset:384
	ds_read_u16 v130, v46 offset:640
	ds_read_u16 v131, v46 offset:896
	ds_read_u16 v132, v46 offset:2176
	ds_read_u16 v133, v46 offset:2432
	ds_read_u16 v134, v46 offset:2688
	ds_read_u16 v135, v46 offset:2944
	ds_read_u16 v136, v46 offset:4224
	ds_read_u16 v137, v46 offset:4480
	ds_read_u16 v138, v46 offset:4736
	ds_read_u16 v139, v46 offset:4992
	ds_read_u16 v140, v46 offset:6272
	ds_read_u16 v141, v46 offset:6528
	ds_read_u16 v142, v46 offset:6784
	ds_read_u16 v143, v46 offset:7040
	s_waitcnt lgkmcnt(0)
	v_mul_f32_e32 v4, v80, v112
	v_lshlrev_b32_e32 v5, 16, v128
	v_fma_f32 v4, -v216, v4, v5
	v_cvt_pk_bf16_f32 v4, v4, v4
	ds_write_b16 v46, v4 offset:128
	v_mul_f32_e32 v4, v81, v113
	v_lshlrev_b32_e32 v5, 16, v129
	v_fma_f32 v4, -v216, v4, v5
	v_cvt_pk_bf16_f32 v4, v4, v4
	ds_write_b16 v46, v4 offset:384
	v_mul_f32_e32 v4, v82, v114
	v_lshlrev_b32_e32 v5, 16, v130
	v_fma_f32 v4, -v216, v4, v5
	v_cvt_pk_bf16_f32 v4, v4, v4
	ds_write_b16 v46, v4 offset:640
	v_mul_f32_e32 v4, v83, v115
	v_lshlrev_b32_e32 v5, 16, v131
	v_fma_f32 v4, -v216, v4, v5
	v_cvt_pk_bf16_f32 v4, v4, v4
	ds_write_b16 v46, v4 offset:896
	v_mul_f32_e32 v4, v84, v116
	v_lshlrev_b32_e32 v5, 16, v132
	v_fma_f32 v4, -v216, v4, v5
	v_cvt_pk_bf16_f32 v4, v4, v4
	ds_write_b16 v46, v4 offset:2176
	v_mul_f32_e32 v4, v85, v117
	v_lshlrev_b32_e32 v5, 16, v133
	v_fma_f32 v4, -v216, v4, v5
	v_cvt_pk_bf16_f32 v4, v4, v4
	ds_write_b16 v46, v4 offset:2432
	v_mul_f32_e32 v4, v86, v118
	v_lshlrev_b32_e32 v5, 16, v134
	v_fma_f32 v4, -v216, v4, v5
	v_cvt_pk_bf16_f32 v4, v4, v4
	ds_write_b16 v46, v4 offset:2688
	v_mul_f32_e32 v4, v87, v119
	v_lshlrev_b32_e32 v5, 16, v135
	v_fma_f32 v4, -v216, v4, v5
	v_cvt_pk_bf16_f32 v4, v4, v4
	ds_write_b16 v46, v4 offset:2944
	v_mul_f32_e32 v4, v88, v120
	v_lshlrev_b32_e32 v5, 16, v136
	v_fma_f32 v4, -v216, v4, v5
	v_cvt_pk_bf16_f32 v4, v4, v4
	ds_write_b16 v46, v4 offset:4224
	v_mul_f32_e32 v4, v89, v121
	v_lshlrev_b32_e32 v5, 16, v137
	v_fma_f32 v4, -v216, v4, v5
	v_cvt_pk_bf16_f32 v4, v4, v4
	ds_write_b16 v46, v4 offset:4480
	v_mul_f32_e32 v4, v90, v122
	v_lshlrev_b32_e32 v5, 16, v138
	v_fma_f32 v4, -v216, v4, v5
	v_cvt_pk_bf16_f32 v4, v4, v4
	ds_write_b16 v46, v4 offset:4736
	v_mul_f32_e32 v4, v91, v123
	v_lshlrev_b32_e32 v5, 16, v139
	v_fma_f32 v4, -v216, v4, v5
	v_cvt_pk_bf16_f32 v4, v4, v4
	ds_write_b16 v46, v4 offset:4992
	v_mul_f32_e32 v4, v92, v124
	v_lshlrev_b32_e32 v5, 16, v140
	v_fma_f32 v4, -v216, v4, v5
	v_cvt_pk_bf16_f32 v4, v4, v4
	ds_write_b16 v46, v4 offset:6272
	v_mul_f32_e32 v4, v93, v125
	v_lshlrev_b32_e32 v5, 16, v141
	v_fma_f32 v4, -v216, v4, v5
	v_cvt_pk_bf16_f32 v4, v4, v4
	ds_write_b16 v46, v4 offset:6528
	v_mul_f32_e32 v4, v94, v126
	v_lshlrev_b32_e32 v5, 16, v142
	v_fma_f32 v4, -v216, v4, v5
	v_cvt_pk_bf16_f32 v4, v4, v4
	ds_write_b16 v46, v4 offset:6784
	v_mul_f32_e32 v4, v95, v127
	v_lshlrev_b32_e32 v5, 16, v143
	v_fma_f32 v4, -v216, v4, v5
	v_cvt_pk_bf16_f32 v4, v4, v4
	ds_write_b16 v46, v4 offset:7040
	ds_read_u16 v128, v46 offset:192
	ds_read_u16 v129, v46 offset:448
	ds_read_u16 v130, v46 offset:704
	ds_read_u16 v131, v46 offset:960
	ds_read_u16 v132, v46 offset:2240
	ds_read_u16 v133, v46 offset:2496
	ds_read_u16 v134, v46 offset:2752
	ds_read_u16 v135, v46 offset:3008
	ds_read_u16 v136, v46 offset:4288
	ds_read_u16 v137, v46 offset:4544
	ds_read_u16 v138, v46 offset:4800
	ds_read_u16 v139, v46 offset:5056
	ds_read_u16 v140, v46 offset:6336
	ds_read_u16 v141, v46 offset:6592
	ds_read_u16 v142, v46 offset:6848
	ds_read_u16 v143, v46 offset:7104
	s_waitcnt lgkmcnt(0)
; __device__ __forceinline__ unsigned cvtpk_s(float lo,float hi){f32x2_t v={lo,hi};bf16x2_t b=__builtin_convertvector(v,bf16x2_t);return __builtin_bit_cast(unsigned,b);}
; #define ATTN_STORE16(p,v) st16_wt((p),(v))
;     ...
;         #pragma unroll
;         for(int d0=0;d0<2;++d0){ const float old=__uint_as_float((unsigned)stl[cr0(r)*64+d0*32]<<16); stl[cr0(r)*64+d0*32]=(bf16)(cvtpk_s(old-lam*(o[d0][r]*rli[r]),0.f)&0xffffu);} }
;     } else {
;       #pragma unroll
;       for(int r=0;r<16;++r){
;         #pragma unroll
;         for(int d0=0;d0<2;++d0)stl[cr0(r)*64+d0*32]=(bf16)(cvtpk_s(o[d0][r]*rli[r],0.f)&0xffffu);}
;     }
;     asm volatile("s_waitcnt lgkmcnt(0)":::"memory");
;     if(emode==0){
;       #pragma unroll
;       for(int i=0;i<4;++i){const int row=i*8+(lane>>3),ch=lane&7; const u32x4 v=*(const u32x4*)(stg+row*64+ch*8); ATTN_STORE16(Ow+(long)row*OP+ch*8,v);}
;     } else if(emode==3){
;       #pragma unroll
;       for(int i=0;i<4;++i){const int row=i*8+(lane>>3),ch=lane&7;
;         const u32x4 v0=*(const u32x4*)(stg+row*64+ch*8), v1=*(const u32x4*)(stg+2048+row*64+ch*8);
;         float f[16]; float ss=0.f;
;         #pragma unroll
;         for(int j=0;j<4;++j){ f[2*j]=__uint_as_float(v0[j]<<16); f[2*j+1]=__uint_as_float(v0[j]&0xffff0000u); f[8+2*j]=__uint_as_float(v1[j]<<16); f[8+2*j+1]=__uint_as_float(v1[j]&0xffff0000u); }
;         #pragma unroll
;         for(int j=0;j<16;++j)ss+=f[j]*f[j];
;         ss+=__shfl_xor(ss,1); ss+=__shfl_xor(ss,2); ss+=__shfl_xor(ss,4);
;         const float rn=__builtin_amdgcn_rsqf(ss*(1.f/128.f)+1e-6f)*0.8f;
;         u32x4 w0,w1;
;         #pragma unroll
;         for(int j=0;j<4;++j){ w0[j]=cvtpk_s(f[2*j]*rn,f[2*j+1]*rn); w1[j]=cvtpk_s(f[8+2*j]*rn,f[8+2*j+1]*rn); }
;         ATTN_STORE16(Ow+(long)row*OP+ch*8,w0); ATTN_STORE16(Ow+(long)row*OP+64+ch*8,w1);}
	v_mul_f32_e32 v4, v96, v112
	v_lshlrev_b32_e32 v5, 16, v128
	v_fma_f32 v4, -v216, v4, v5
	v_cvt_pk_bf16_f32 v4, v4, v4
	ds_write_b16 v46, v4 offset:192
	v_mul_f32_e32 v4, v97, v113
	v_lshlrev_b32_e32 v5, 16, v129
	v_fma_f32 v4, -v216, v4, v5
	v_cvt_pk_bf16_f32 v4, v4, v4
	ds_write_b16 v46, v4 offset:448
	v_mul_f32_e32 v4, v98, v114
	v_lshlrev_b32_e32 v5, 16, v130
	v_fma_f32 v4, -v216, v4, v5
	v_cvt_pk_bf16_f32 v4, v4, v4
	ds_write_b16 v46, v4 offset:704
	v_mul_f32_e32 v4, v99, v115
	v_lshlrev_b32_e32 v5, 16, v131
	v_fma_f32 v4, -v216, v4, v5
	v_cvt_pk_bf16_f32 v4, v4, v4
	ds_write_b16 v46, v4 offset:960
	v_mul_f32_e32 v4, v100, v116
	v_lshlrev_b32_e32 v5, 16, v132
	v_fma_f32 v4, -v216, v4, v5
	v_cvt_pk_bf16_f32 v4, v4, v4
	ds_write_b16 v46, v4 offset:2240
	v_mul_f32_e32 v4, v101, v117
	v_lshlrev_b32_e32 v5, 16, v133
	v_fma_f32 v4, -v216, v4, v5
	v_cvt_pk_bf16_f32 v4, v4, v4
	ds_write_b16 v46, v4 offset:2496
	v_mul_f32_e32 v4, v102, v118
	v_lshlrev_b32_e32 v5, 16, v134
	v_fma_f32 v4, -v216, v4, v5
	v_cvt_pk_bf16_f32 v4, v4, v4
	ds_write_b16 v46, v4 offset:2752
	v_mul_f32_e32 v4, v103, v119
	v_lshlrev_b32_e32 v5, 16, v135
	v_fma_f32 v4, -v216, v4, v5
	v_cvt_pk_bf16_f32 v4, v4, v4
	ds_write_b16 v46, v4 offset:3008
	v_mul_f32_e32 v4, v104, v120
	v_lshlrev_b32_e32 v5, 16, v136
	v_fma_f32 v4, -v216, v4, v5
	v_cvt_pk_bf16_f32 v4, v4, v4
	ds_write_b16 v46, v4 offset:4288
	v_mul_f32_e32 v4, v105, v121
	v_lshlrev_b32_e32 v5, 16, v137
	v_fma_f32 v4, -v216, v4, v5
	v_cvt_pk_bf16_f32 v4, v4, v4
	ds_write_b16 v46, v4 offset:4544
	v_mul_f32_e32 v4, v106, v122
	v_lshlrev_b32_e32 v5, 16, v138
	v_fma_f32 v4, -v216, v4, v5
	v_cvt_pk_bf16_f32 v4, v4, v4
	ds_write_b16 v46, v4 offset:4800
	v_mul_f32_e32 v4, v107, v123
	v_lshlrev_b32_e32 v5, 16, v139
	v_fma_f32 v4, -v216, v4, v5
	v_cvt_pk_bf16_f32 v4, v4, v4
	ds_write_b16 v46, v4 offset:5056
	v_mul_f32_e32 v4, v108, v124
	v_lshlrev_b32_e32 v5, 16, v140
	v_fma_f32 v4, -v216, v4, v5
	v_cvt_pk_bf16_f32 v4, v4, v4
	ds_write_b16 v46, v4 offset:6336
	v_mul_f32_e32 v4, v109, v125
	v_lshlrev_b32_e32 v5, 16, v141
	v_fma_f32 v4, -v216, v4, v5
	v_cvt_pk_bf16_f32 v4, v4, v4
	ds_write_b16 v46, v4 offset:6592
	v_mul_f32_e32 v4, v110, v126
	v_lshlrev_b32_e32 v5, 16, v142
	v_fma_f32 v4, -v216, v4, v5
	v_cvt_pk_bf16_f32 v4, v4, v4
	ds_write_b16 v46, v4 offset:6848
	v_mul_f32_e32 v4, v111, v127
	v_lshlrev_b32_e32 v5, 16, v143
	v_fma_f32 v4, -v216, v4, v5
	v_cvt_pk_bf16_f32 v4, v4, v4
	ds_write_b16 v46, v4 offset:7104
	s_waitcnt lgkmcnt(0)
	ds_read_b128 v[176:179], v219 offset:0
	ds_read_b128 v[180:183], v219 offset:1024
	ds_read_b128 v[184:187], v219 offset:2048
	ds_read_b128 v[188:191], v219 offset:3072
	ds_read_b128 v[192:195], v219 offset:4096
	ds_read_b128 v[196:199], v219 offset:5120
	ds_read_b128 v[200:203], v219 offset:6144
	ds_read_b128 v[204:207], v219 offset:7168
	s_waitcnt lgkmcnt(0)
	v_mov_b32_e32 v37, 0x3c000000
	v_mov_b32_e32 v38, 0x358637bd
	v_lshlrev_b32_e32 v112, 16, v176
	v_and_b32_e32 v113, 0xffff0000, v176
	v_lshlrev_b32_e32 v114, 16, v177
	v_and_b32_e32 v115, 0xffff0000, v177
	v_lshlrev_b32_e32 v116, 16, v178
	v_and_b32_e32 v117, 0xffff0000, v178
	v_lshlrev_b32_e32 v118, 16, v179
	v_and_b32_e32 v119, 0xffff0000, v179
	v_mul_f32_e32 v4, v112, v112
	v_fmac_f32_e32 v4, v113, v113
	v_fmac_f32_e32 v4, v114, v114
	v_fmac_f32_e32 v4, v115, v115
	v_fmac_f32_e32 v4, v116, v116
	v_fmac_f32_e32 v4, v117, v117
	v_fmac_f32_e32 v4, v118, v118
	v_fmac_f32_e32 v4, v119, v119
	s_nop 1
	v_mov_b32_dpp v5, v4 row_ror:8 row_mask:0xf bank_mask:0xf
	v_add_f32_e32 v4, v4, v5
	s_nop 1
	v_mov_b32_dpp v5, v4 row_ror:4 row_mask:0xf bank_mask:0xf
	v_add_f32_e32 v4, v4, v5
	s_nop 1
	v_mov_b32_dpp v5, v4 row_ror:2 row_mask:0xf bank_mask:0xf
	v_add_f32_e32 v4, v4, v5
	s_nop 1
	v_mov_b32_dpp v5, v4 row_ror:1 row_mask:0xf bank_mask:0xf
	v_add_f32_e32 v4, v4, v5
	v_fma_f32 v4, v4, v37, v38
	v_rsq_f32_e32 v4, v4
	s_nop 0
	v_mul_f32_e32 v4, 0x3f4ccccd, v4
	v_mul_f32_e32 v112, v112, v4
	v_mul_f32_e32 v113, v113, v4
	v_mul_f32_e32 v114, v114, v4
	v_mul_f32_e32 v115, v115, v4
	v_mul_f32_e32 v116, v116, v4
	v_mul_f32_e32 v117, v117, v4
	v_mul_f32_e32 v118, v118, v4
	v_mul_f32_e32 v119, v119, v4
	v_cvt_pk_bf16_f32 v176, v112, v113
	v_cvt_pk_bf16_f32 v177, v114, v115
	v_cvt_pk_bf16_f32 v178, v116, v117
	v_cvt_pk_bf16_f32 v179, v118, v119
	v_mov_b32_e32 v253, v252
	global_store_dwordx4 v253, v[176:179], s[86:87]
	v_lshlrev_b32_e32 v112, 16, v180
	v_and_b32_e32 v113, 0xffff0000, v180
	v_lshlrev_b32_e32 v114, 16, v181
	v_and_b32_e32 v115, 0xffff0000, v181
	v_lshlrev_b32_e32 v116, 16, v182
	v_and_b32_e32 v117, 0xffff0000, v182
	v_lshlrev_b32_e32 v118, 16, v183
	v_and_b32_e32 v119, 0xffff0000, v183
	v_mul_f32_e32 v4, v112, v112
	v_fmac_f32_e32 v4, v113, v113
	v_fmac_f32_e32 v4, v114, v114
	v_fmac_f32_e32 v4, v115, v115
	v_fmac_f32_e32 v4, v116, v116
	v_fmac_f32_e32 v4, v117, v117
	v_fmac_f32_e32 v4, v118, v118
	v_fmac_f32_e32 v4, v119, v119
	s_nop 1
	v_mov_b32_dpp v5, v4 row_ror:8 row_mask:0xf bank_mask:0xf
	v_add_f32_e32 v4, v4, v5
	s_nop 1
	v_mov_b32_dpp v5, v4 row_ror:4 row_mask:0xf bank_mask:0xf
	v_add_f32_e32 v4, v4, v5
	s_nop 1
	v_mov_b32_dpp v5, v4 row_ror:2 row_mask:0xf bank_mask:0xf
	v_add_f32_e32 v4, v4, v5
	s_nop 1
	v_mov_b32_dpp v5, v4 row_ror:1 row_mask:0xf bank_mask:0xf
	v_add_f32_e32 v4, v4, v5
	v_fma_f32 v4, v4, v37, v38
	v_rsq_f32_e32 v4, v4
	s_nop 0
	v_mul_f32_e32 v4, 0x3f4ccccd, v4
	v_mul_f32_e32 v112, v112, v4
	v_mul_f32_e32 v113, v113, v4
	v_mul_f32_e32 v114, v114, v4
	v_mul_f32_e32 v115, v115, v4
	v_mul_f32_e32 v116, v116, v4
	v_mul_f32_e32 v117, v117, v4
	v_mul_f32_e32 v118, v118, v4
	v_mul_f32_e32 v119, v119, v4
; __device__ __forceinline__ unsigned cvtpk_s(float lo,float hi){f32x2_t v={lo,hi};bf16x2_t b=__builtin_convertvector(v,bf16x2_t);return __builtin_bit_cast(unsigned,b);}
; #define ATTN_STORE16(p,v) st16_wt((p),(v))
;     ...
;     } else if(emode==3){
;       #pragma unroll
;       for(int i=0;i<4;++i){const int row=i*8+(lane>>3),ch=lane&7;
;         const u32x4 v0=*(const u32x4*)(stg+row*64+ch*8), v1=*(const u32x4*)(stg+2048+row*64+ch*8);
;         float f[16]; float ss=0.f;
;         #pragma unroll
;         for(int j=0;j<4;++j){ f[2*j]=__uint_as_float(v0[j]<<16); f[2*j+1]=__uint_as_float(v0[j]&0xffff0000u); f[8+2*j]=__uint_as_float(v1[j]<<16); f[8+2*j+1]=__uint_as_float(v1[j]&0xffff0000u); }
;         #pragma unroll
;         for(int j=0;j<16;++j)ss+=f[j]*f[j];
;         ss+=__shfl_xor(ss,1); ss+=__shfl_xor(ss,2); ss+=__shfl_xor(ss,4);
;         const float rn=__builtin_amdgcn_rsqf(ss*(1.f/128.f)+1e-6f)*0.8f;
;         u32x4 w0,w1;
;         #pragma unroll
;         for(int j=0;j<4;++j){ w0[j]=cvtpk_s(f[2*j]*rn,f[2*j+1]*rn); w1[j]=cvtpk_s(f[8+2*j]*rn,f[8+2*j+1]*rn); }
;         ATTN_STORE16(Ow+(long)row*OP+ch*8,w0); ATTN_STORE16(Ow+(long)row*OP+64+ch*8,w1);}
	v_cvt_pk_bf16_f32 v180, v112, v113
	v_cvt_pk_bf16_f32 v181, v114, v115
	v_cvt_pk_bf16_f32 v182, v116, v117
	v_cvt_pk_bf16_f32 v183, v118, v119
	v_add_u32_e32 v253, 0x2000, v253
	global_store_dwordx4 v253, v[180:183], s[86:87]
	v_lshlrev_b32_e32 v112, 16, v184
	v_and_b32_e32 v113, 0xffff0000, v184
	v_lshlrev_b32_e32 v114, 16, v185
	v_and_b32_e32 v115, 0xffff0000, v185
	v_lshlrev_b32_e32 v116, 16, v186
	v_and_b32_e32 v117, 0xffff0000, v186
	v_lshlrev_b32_e32 v118, 16, v187
	v_and_b32_e32 v119, 0xffff0000, v187
	v_mul_f32_e32 v4, v112, v112
	v_fmac_f32_e32 v4, v113, v113
	v_fmac_f32_e32 v4, v114, v114
	v_fmac_f32_e32 v4, v115, v115
	v_fmac_f32_e32 v4, v116, v116
	v_fmac_f32_e32 v4, v117, v117
	v_fmac_f32_e32 v4, v118, v118
	v_fmac_f32_e32 v4, v119, v119
	s_nop 1
	v_mov_b32_dpp v5, v4 row_ror:8 row_mask:0xf bank_mask:0xf
	v_add_f32_e32 v4, v4, v5
	s_nop 1
	v_mov_b32_dpp v5, v4 row_ror:4 row_mask:0xf bank_mask:0xf
	v_add_f32_e32 v4, v4, v5
	s_nop 1
	v_mov_b32_dpp v5, v4 row_ror:2 row_mask:0xf bank_mask:0xf
	v_add_f32_e32 v4, v4, v5
	s_nop 1
	v_mov_b32_dpp v5, v4 row_ror:1 row_mask:0xf bank_mask:0xf
	v_add_f32_e32 v4, v4, v5
	v_fma_f32 v4, v4, v37, v38
	v_rsq_f32_e32 v4, v4
	s_nop 0
	v_mul_f32_e32 v4, 0x3f4ccccd, v4
	v_mul_f32_e32 v112, v112, v4
	v_mul_f32_e32 v113, v113, v4
	v_mul_f32_e32 v114, v114, v4
	v_mul_f32_e32 v115, v115, v4
	v_mul_f32_e32 v116, v116, v4
	v_mul_f32_e32 v117, v117, v4
	v_mul_f32_e32 v118, v118, v4
	v_mul_f32_e32 v119, v119, v4
	v_cvt_pk_bf16_f32 v184, v112, v113
	v_cvt_pk_bf16_f32 v185, v114, v115
	v_cvt_pk_bf16_f32 v186, v116, v117
	v_cvt_pk_bf16_f32 v187, v118, v119
	v_add_u32_e32 v253, 0x2000, v253
	global_store_dwordx4 v253, v[184:187], s[86:87]
	v_lshlrev_b32_e32 v112, 16, v188
	v_and_b32_e32 v113, 0xffff0000, v188
	v_lshlrev_b32_e32 v114, 16, v189
	v_and_b32_e32 v115, 0xffff0000, v189
	v_lshlrev_b32_e32 v116, 16, v190
	v_and_b32_e32 v117, 0xffff0000, v190
	v_lshlrev_b32_e32 v118, 16, v191
	v_and_b32_e32 v119, 0xffff0000, v191
	v_mul_f32_e32 v4, v112, v112
	v_fmac_f32_e32 v4, v113, v113
	v_fmac_f32_e32 v4, v114, v114
	v_fmac_f32_e32 v4, v115, v115
	v_fmac_f32_e32 v4, v116, v116
	v_fmac_f32_e32 v4, v117, v117
	v_fmac_f32_e32 v4, v118, v118
	v_fmac_f32_e32 v4, v119, v119
	s_nop 1
	v_mov_b32_dpp v5, v4 row_ror:8 row_mask:0xf bank_mask:0xf
	v_add_f32_e32 v4, v4, v5
	s_nop 1
	v_mov_b32_dpp v5, v4 row_ror:4 row_mask:0xf bank_mask:0xf
	v_add_f32_e32 v4, v4, v5
	s_nop 1
	v_mov_b32_dpp v5, v4 row_ror:2 row_mask:0xf bank_mask:0xf
	v_add_f32_e32 v4, v4, v5
	s_nop 1
	v_mov_b32_dpp v5, v4 row_ror:1 row_mask:0xf bank_mask:0xf
	v_add_f32_e32 v4, v4, v5
	v_fma_f32 v4, v4, v37, v38
	v_rsq_f32_e32 v4, v4
	s_nop 0
	v_mul_f32_e32 v4, 0x3f4ccccd, v4
	v_mul_f32_e32 v112, v112, v4
	v_mul_f32_e32 v113, v113, v4
	v_mul_f32_e32 v114, v114, v4
	v_mul_f32_e32 v115, v115, v4
	v_mul_f32_e32 v116, v116, v4
	v_mul_f32_e32 v117, v117, v4
	v_mul_f32_e32 v118, v118, v4
	v_mul_f32_e32 v119, v119, v4
	v_cvt_pk_bf16_f32 v188, v112, v113
	v_cvt_pk_bf16_f32 v189, v114, v115
	v_cvt_pk_bf16_f32 v190, v116, v117
	v_cvt_pk_bf16_f32 v191, v118, v119
	v_add_u32_e32 v253, 0x2000, v253
	global_store_dwordx4 v253, v[188:191], s[86:87]
	v_lshlrev_b32_e32 v112, 16, v192
	v_and_b32_e32 v113, 0xffff0000, v192
	v_lshlrev_b32_e32 v114, 16, v193
	v_and_b32_e32 v115, 0xffff0000, v193
	v_lshlrev_b32_e32 v116, 16, v194
	v_and_b32_e32 v117, 0xffff0000, v194
	v_lshlrev_b32_e32 v118, 16, v195
	v_and_b32_e32 v119, 0xffff0000, v195
	v_mul_f32_e32 v4, v112, v112
	v_fmac_f32_e32 v4, v113, v113
	v_fmac_f32_e32 v4, v114, v114
	v_fmac_f32_e32 v4, v115, v115
	v_fmac_f32_e32 v4, v116, v116
	v_fmac_f32_e32 v4, v117, v117
	v_fmac_f32_e32 v4, v118, v118
	v_fmac_f32_e32 v4, v119, v119
	s_nop 1
	v_mov_b32_dpp v5, v4 row_ror:8 row_mask:0xf bank_mask:0xf
	v_add_f32_e32 v4, v4, v5
	s_nop 1
	v_mov_b32_dpp v5, v4 row_ror:4 row_mask:0xf bank_mask:0xf
	v_add_f32_e32 v4, v4, v5
	s_nop 1
	v_mov_b32_dpp v5, v4 row_ror:2 row_mask:0xf bank_mask:0xf
	v_add_f32_e32 v4, v4, v5
	s_nop 1
	v_mov_b32_dpp v5, v4 row_ror:1 row_mask:0xf bank_mask:0xf
	v_add_f32_e32 v4, v4, v5
	v_fma_f32 v4, v4, v37, v38
	v_rsq_f32_e32 v4, v4
	s_nop 0
	v_mul_f32_e32 v4, 0x3f4ccccd, v4
	v_mul_f32_e32 v112, v112, v4
	v_mul_f32_e32 v113, v113, v4
	v_mul_f32_e32 v114, v114, v4
	v_mul_f32_e32 v115, v115, v4
	v_mul_f32_e32 v116, v116, v4
	v_mul_f32_e32 v117, v117, v4
	v_mul_f32_e32 v118, v118, v4
	v_mul_f32_e32 v119, v119, v4
	v_cvt_pk_bf16_f32 v192, v112, v113
	v_cvt_pk_bf16_f32 v193, v114, v115
	v_cvt_pk_bf16_f32 v194, v116, v117
	v_cvt_pk_bf16_f32 v195, v118, v119
; __device__ __forceinline__ unsigned cvtpk_s(float lo,float hi){f32x2_t v={lo,hi};bf16x2_t b=__builtin_convertvector(v,bf16x2_t);return __builtin_bit_cast(unsigned,b);}
; #define ATTN_STORE16(p,v) st16_wt((p),(v))
;     ...
;     } else if(emode==3){
;       #pragma unroll
;       for(int i=0;i<4;++i){const int row=i*8+(lane>>3),ch=lane&7;
;         const u32x4 v0=*(const u32x4*)(stg+row*64+ch*8), v1=*(const u32x4*)(stg+2048+row*64+ch*8);
;         float f[16]; float ss=0.f;
;         #pragma unroll
;         for(int j=0;j<4;++j){ f[2*j]=__uint_as_float(v0[j]<<16); f[2*j+1]=__uint_as_float(v0[j]&0xffff0000u); f[8+2*j]=__uint_as_float(v1[j]<<16); f[8+2*j+1]=__uint_as_float(v1[j]&0xffff0000u); }
;         #pragma unroll
;         for(int j=0;j<16;++j)ss+=f[j]*f[j];
;         ss+=__shfl_xor(ss,1); ss+=__shfl_xor(ss,2); ss+=__shfl_xor(ss,4);
;         const float rn=__builtin_amdgcn_rsqf(ss*(1.f/128.f)+1e-6f)*0.8f;
;         u32x4 w0,w1;
;         #pragma unroll
;         for(int j=0;j<4;++j){ w0[j]=cvtpk_s(f[2*j]*rn,f[2*j+1]*rn); w1[j]=cvtpk_s(f[8+2*j]*rn,f[8+2*j+1]*rn); }
;         ATTN_STORE16(Ow+(long)row*OP+ch*8,w0); ATTN_STORE16(Ow+(long)row*OP+64+ch*8,w1);}
;     }
;   }
;   asm volatile("s_waitcnt lgkmcnt(0)\n\ts_barrier":::"memory");
	v_add_u32_e32 v253, 0x2000, v253
	global_store_dwordx4 v253, v[192:195], s[86:87]
	v_lshlrev_b32_e32 v112, 16, v196
	v_and_b32_e32 v113, 0xffff0000, v196
	v_lshlrev_b32_e32 v114, 16, v197
	v_and_b32_e32 v115, 0xffff0000, v197
	v_lshlrev_b32_e32 v116, 16, v198
	v_and_b32_e32 v117, 0xffff0000, v198
	v_lshlrev_b32_e32 v118, 16, v199
	v_and_b32_e32 v119, 0xffff0000, v199
	v_mul_f32_e32 v4, v112, v112
	v_fmac_f32_e32 v4, v113, v113
	v_fmac_f32_e32 v4, v114, v114
	v_fmac_f32_e32 v4, v115, v115
	v_fmac_f32_e32 v4, v116, v116
	v_fmac_f32_e32 v4, v117, v117
	v_fmac_f32_e32 v4, v118, v118
	v_fmac_f32_e32 v4, v119, v119
	s_nop 1
	v_mov_b32_dpp v5, v4 row_ror:8 row_mask:0xf bank_mask:0xf
	v_add_f32_e32 v4, v4, v5
	s_nop 1
	v_mov_b32_dpp v5, v4 row_ror:4 row_mask:0xf bank_mask:0xf
	v_add_f32_e32 v4, v4, v5
	s_nop 1
	v_mov_b32_dpp v5, v4 row_ror:2 row_mask:0xf bank_mask:0xf
	v_add_f32_e32 v4, v4, v5
	s_nop 1
	v_mov_b32_dpp v5, v4 row_ror:1 row_mask:0xf bank_mask:0xf
	v_add_f32_e32 v4, v4, v5
	v_fma_f32 v4, v4, v37, v38
	v_rsq_f32_e32 v4, v4
	s_nop 0
	v_mul_f32_e32 v4, 0x3f4ccccd, v4
	v_mul_f32_e32 v112, v112, v4
	v_mul_f32_e32 v113, v113, v4
	v_mul_f32_e32 v114, v114, v4
	v_mul_f32_e32 v115, v115, v4
	v_mul_f32_e32 v116, v116, v4
	v_mul_f32_e32 v117, v117, v4
	v_mul_f32_e32 v118, v118, v4
	v_mul_f32_e32 v119, v119, v4
	v_cvt_pk_bf16_f32 v196, v112, v113
	v_cvt_pk_bf16_f32 v197, v114, v115
	v_cvt_pk_bf16_f32 v198, v116, v117
	v_cvt_pk_bf16_f32 v199, v118, v119
	v_add_u32_e32 v253, 0x2000, v253
	global_store_dwordx4 v253, v[196:199], s[86:87]
	v_lshlrev_b32_e32 v112, 16, v200
	v_and_b32_e32 v113, 0xffff0000, v200
	v_lshlrev_b32_e32 v114, 16, v201
	v_and_b32_e32 v115, 0xffff0000, v201
	v_lshlrev_b32_e32 v116, 16, v202
	v_and_b32_e32 v117, 0xffff0000, v202
	v_lshlrev_b32_e32 v118, 16, v203
	v_and_b32_e32 v119, 0xffff0000, v203
	v_mul_f32_e32 v4, v112, v112
	v_fmac_f32_e32 v4, v113, v113
	v_fmac_f32_e32 v4, v114, v114
	v_fmac_f32_e32 v4, v115, v115
	v_fmac_f32_e32 v4, v116, v116
	v_fmac_f32_e32 v4, v117, v117
	v_fmac_f32_e32 v4, v118, v118
	v_fmac_f32_e32 v4, v119, v119
	s_nop 1
	v_mov_b32_dpp v5, v4 row_ror:8 row_mask:0xf bank_mask:0xf
	v_add_f32_e32 v4, v4, v5
	s_nop 1
	v_mov_b32_dpp v5, v4 row_ror:4 row_mask:0xf bank_mask:0xf
	v_add_f32_e32 v4, v4, v5
	s_nop 1
	v_mov_b32_dpp v5, v4 row_ror:2 row_mask:0xf bank_mask:0xf
	v_add_f32_e32 v4, v4, v5
	s_nop 1
	v_mov_b32_dpp v5, v4 row_ror:1 row_mask:0xf bank_mask:0xf
	v_add_f32_e32 v4, v4, v5
	v_fma_f32 v4, v4, v37, v38
	v_rsq_f32_e32 v4, v4
	s_nop 0
	v_mul_f32_e32 v4, 0x3f4ccccd, v4
	v_mul_f32_e32 v112, v112, v4
	v_mul_f32_e32 v113, v113, v4
	v_mul_f32_e32 v114, v114, v4
	v_mul_f32_e32 v115, v115, v4
	v_mul_f32_e32 v116, v116, v4
	v_mul_f32_e32 v117, v117, v4
	v_mul_f32_e32 v118, v118, v4
	v_mul_f32_e32 v119, v119, v4
	v_cvt_pk_bf16_f32 v200, v112, v113
	v_cvt_pk_bf16_f32 v201, v114, v115
	v_cvt_pk_bf16_f32 v202, v116, v117
	v_cvt_pk_bf16_f32 v203, v118, v119
	v_add_u32_e32 v253, 0x2000, v253
	global_store_dwordx4 v253, v[200:203], s[86:87]
	v_lshlrev_b32_e32 v112, 16, v204
	v_and_b32_e32 v113, 0xffff0000, v204
	v_lshlrev_b32_e32 v114, 16, v205
	v_and_b32_e32 v115, 0xffff0000, v205
	v_lshlrev_b32_e32 v116, 16, v206
	v_and_b32_e32 v117, 0xffff0000, v206
	v_lshlrev_b32_e32 v118, 16, v207
	v_and_b32_e32 v119, 0xffff0000, v207
	v_mul_f32_e32 v4, v112, v112
	v_fmac_f32_e32 v4, v113, v113
	v_fmac_f32_e32 v4, v114, v114
	v_fmac_f32_e32 v4, v115, v115
	v_fmac_f32_e32 v4, v116, v116
	v_fmac_f32_e32 v4, v117, v117
	v_fmac_f32_e32 v4, v118, v118
	v_fmac_f32_e32 v4, v119, v119
	s_nop 1
	v_mov_b32_dpp v5, v4 row_ror:8 row_mask:0xf bank_mask:0xf
	v_add_f32_e32 v4, v4, v5
	s_nop 1
	v_mov_b32_dpp v5, v4 row_ror:4 row_mask:0xf bank_mask:0xf
	v_add_f32_e32 v4, v4, v5
	s_nop 1
	v_mov_b32_dpp v5, v4 row_ror:2 row_mask:0xf bank_mask:0xf
	v_add_f32_e32 v4, v4, v5
	s_nop 1
	v_mov_b32_dpp v5, v4 row_ror:1 row_mask:0xf bank_mask:0xf
	v_add_f32_e32 v4, v4, v5
	v_fma_f32 v4, v4, v37, v38
	v_rsq_f32_e32 v4, v4
	s_nop 0
	v_mul_f32_e32 v4, 0x3f4ccccd, v4
	v_mul_f32_e32 v112, v112, v4
	v_mul_f32_e32 v113, v113, v4
	v_mul_f32_e32 v114, v114, v4
	v_mul_f32_e32 v115, v115, v4
	v_mul_f32_e32 v116, v116, v4
	v_mul_f32_e32 v117, v117, v4
	v_mul_f32_e32 v118, v118, v4
	v_mul_f32_e32 v119, v119, v4
	v_cvt_pk_bf16_f32 v204, v112, v113
	v_cvt_pk_bf16_f32 v205, v114, v115
	v_cvt_pk_bf16_f32 v206, v116, v117
	v_cvt_pk_bf16_f32 v207, v118, v119
	v_add_u32_e32 v253, 0x2000, v253
	global_store_dwordx4 v253, v[204:207], s[86:87]
	s_waitcnt lgkmcnt(0)
	s_branch .LBB0_1511
